# LRU table build with all 11 loads in flight; adaLN GEMV inner loop rewritten with 32-48 loads in flight
# speedup vs baseline: 1.0120x; 1.0087x over previous
.LBB0_299:
	s_load_dwordx2 s[10:11], s[0:1], 0x48
	s_load_dwordx2 s[12:13], s[0:1], 0x50
	s_load_dwordx2 s[14:15], s[0:1], 0x60
	s_load_dwordx2 s[16:17], s[0:1], 0x70
	s_load_dwordx2 s[18:19], s[0:1], 0x78
	v_lshlrev_b32_e32 v2, 2, v200
	s_lshl_b32 s4, s24, 2
	s_add_i32 s5, s25, 0x800
	s_lshl_b32 s5, s5, 2
	s_lshl_b32 s8, s23, 2
	s_waitcnt lgkmcnt(0)
	s_add_u32 s10, s10, s4
	s_addc_u32 s11, s11, 0
	s_add_u32 s20, s10, 0x1000
	s_addc_u32 s21, s11, 0
	s_add_u32 s12, s12, s5
	s_addc_u32 s13, s13, 0
	s_add_u32 s14, s14, s8
	s_addc_u32 s15, s15, 0
	s_add_u32 s16, s16, s8
	s_addc_u32 s17, s17, 0
	s_add_u32 s18, s18, s8
	s_addc_u32 s19, s19, 0
	global_load_dword v3, v2, s[10:11]
	global_load_dword v4, v2, s[10:11] offset:2048
	global_load_dword v5, v2, s[20:21]
	global_load_dword v6, v2, s[20:21] offset:2048
	global_load_dword v7, v2, s[12:13]
	global_load_dword v8, v2, s[14:15]
	global_load_dword v9, v2, s[14:15] offset:2048
	global_load_dword v10, v2, s[16:17]
	global_load_dword v11, v2, s[16:17] offset:2048
	global_load_dword v12, v2, s[18:19]
	global_load_dword v13, v2, s[18:19] offset:2048
	s_waitcnt vmcnt(0)
	ds_write_b32 v0, v3
	ds_write_b32 v0, v4 offset:2048
	ds_write_b32 v0, v5 offset:4096
	ds_write_b32 v0, v6 offset:6144
	ds_write_b32 v0, v7 offset:8192
	v_mul_f32_e32 v8, 0xbfb8aa3b, v8
	v_mul_f32_e32 v9, 0xbfb8aa3b, v9
	v_mul_f32_e32 v10, 0xbfb8aa3b, v10
	v_mul_f32_e32 v11, 0xbfb8aa3b, v11
	ds_write_b32 v0, v8 offset:10240
	ds_write_b32 v0, v9 offset:12288
	ds_write_b32 v0, v10 offset:14336
	ds_write_b32 v0, v11 offset:16384
	v_mul_f32_e32 v14, 0xbfb8aa3b, v12
	v_exp_f32_e32 v14, v14
	v_mov_b32_e32 v16, 0x3eaaaaab
	v_add_f32_e32 v15, 1.0, v14
	v_log_f32_e32 v15, v15
	v_fmamk_f32 v16, v14, 0xbe800000, v16
	v_fma_f32 v16, -v14, v16, 0.5
	v_fma_f32 v16, -v14, v16, 1.0
	v_mul_f32_e32 v16, v14, v16
	v_mul_f32_e32 v15, 0x3f317218, v15
	s_mov_b32 s4, 0xc1a00000
	v_cmp_ngt_f32_e32 vcc, s4, v12
	v_xor_b32_e32 v12, 0x80000000, v12
	s_mov_b32 s4, 0x3cf5c28f
	v_cndmask_b32_e32 v15, v12, v15, vcc
	v_cmp_ngt_f32_e32 vcc, s4, v14
	s_nop 1
	v_cndmask_b32_e32 v15, v16, v15, vcc
	v_mul_f32_e32 v15, 0xc1000000, v15
	v_mul_f32_e32 v15, 0x3fb8aa3b, v15
	ds_write_b32 v0, v15 offset:18432
	v_mul_f32_e32 v17, 0xbfb8aa3b, v13
	v_exp_f32_e32 v17, v17
	v_mov_b32_e32 v19, 0x3eaaaaab
	v_add_f32_e32 v18, 1.0, v17
	v_log_f32_e32 v18, v18
	v_fmamk_f32 v19, v17, 0xbe800000, v19
	v_fma_f32 v19, -v17, v19, 0.5
	v_fma_f32 v19, -v17, v19, 1.0
	v_mul_f32_e32 v19, v17, v19
	v_mul_f32_e32 v18, 0x3f317218, v18
	s_mov_b32 s4, 0xc1a00000
	v_cmp_ngt_f32_e32 vcc, s4, v13
	v_xor_b32_e32 v13, 0x80000000, v13
	s_mov_b32 s4, 0x3cf5c28f
	v_cndmask_b32_e32 v18, v13, v18, vcc
	v_cmp_ngt_f32_e32 vcc, s4, v17
	s_nop 1
	v_cndmask_b32_e32 v18, v19, v18, vcc
	v_mul_f32_e32 v18, 0xc1000000, v18
	v_mul_f32_e32 v18, 0x3fb8aa3b, v18
	ds_write_b32 v0, v18 offset:20480

.LBB0_579:
	s_mov_b64 s[10:11], s[8:9]
	v_mov_b32_e32 v86, s13
	global_load_dword v6, v62, s[10:11] nt
	s_add_u32 s10, s10, 0x6000
	s_addc_u32 s11, s11, 0
	global_load_dword v7, v62, s[10:11] nt
	s_add_u32 s10, s10, 0x6000
	s_addc_u32 s11, s11, 0
	global_load_dword v8, v62, s[10:11] nt
	s_add_u32 s10, s10, 0x6000
	s_addc_u32 s11, s11, 0
	global_load_dword v9, v62, s[10:11] nt
	s_add_u32 s10, s10, 0x6000
	s_addc_u32 s11, s11, 0
	global_load_dword v10, v62, s[10:11] nt
	s_add_u32 s10, s10, 0x6000
	s_addc_u32 s11, s11, 0
	global_load_dword v11, v62, s[10:11] nt
	s_add_u32 s10, s10, 0x6000
	s_addc_u32 s11, s11, 0
	global_load_dword v12, v62, s[10:11] nt
	s_add_u32 s10, s10, 0x6000
	s_addc_u32 s11, s11, 0
	global_load_dword v13, v62, s[10:11] nt
	s_add_u32 s10, s10, 0x6000
	s_addc_u32 s11, s11, 0
	global_load_dword v14, v62, s[10:11] nt
	s_add_u32 s10, s10, 0x6000
	s_addc_u32 s11, s11, 0
	global_load_dword v15, v62, s[10:11] nt
	s_add_u32 s10, s10, 0x6000
	s_addc_u32 s11, s11, 0
	global_load_dword v16, v62, s[10:11] nt
	s_add_u32 s10, s10, 0x6000
	s_addc_u32 s11, s11, 0
	global_load_dword v17, v62, s[10:11] nt
	s_add_u32 s10, s10, 0x6000
	s_addc_u32 s11, s11, 0
	global_load_dword v18, v62, s[10:11] nt
	s_add_u32 s10, s10, 0x6000
	s_addc_u32 s11, s11, 0
	global_load_dword v19, v62, s[10:11] nt
	s_add_u32 s10, s10, 0x6000
	s_addc_u32 s11, s11, 0
	global_load_dword v20, v62, s[10:11] nt
	s_add_u32 s10, s10, 0x6000
	s_addc_u32 s11, s11, 0
	global_load_dword v21, v62, s[10:11] nt
	s_add_u32 s10, s10, 0x6000
	s_addc_u32 s11, s11, 0
	global_load_dword v22, v62, s[10:11] nt
	s_add_u32 s10, s10, 0x6000
	s_addc_u32 s11, s11, 0
	global_load_dword v23, v62, s[10:11] nt
	s_add_u32 s10, s10, 0x6000
	s_addc_u32 s11, s11, 0
	global_load_dword v24, v62, s[10:11] nt
	s_add_u32 s10, s10, 0x6000
	s_addc_u32 s11, s11, 0
	global_load_dword v25, v62, s[10:11] nt
	s_add_u32 s10, s10, 0x6000
	s_addc_u32 s11, s11, 0
	global_load_dword v26, v62, s[10:11] nt
	s_add_u32 s10, s10, 0x6000
	s_addc_u32 s11, s11, 0
	global_load_dword v27, v62, s[10:11] nt
	s_add_u32 s10, s10, 0x6000
	s_addc_u32 s11, s11, 0
	global_load_dword v28, v62, s[10:11] nt
	s_add_u32 s10, s10, 0x6000
	s_addc_u32 s11, s11, 0
	global_load_dword v29, v62, s[10:11] nt
	s_add_u32 s10, s10, 0x6000
	s_addc_u32 s11, s11, 0
	global_load_dword v30, v62, s[10:11] nt
	s_add_u32 s10, s10, 0x6000
	s_addc_u32 s11, s11, 0
	global_load_dword v31, v62, s[10:11] nt
	s_add_u32 s10, s10, 0x6000
	s_addc_u32 s11, s11, 0
	global_load_dword v32, v62, s[10:11] nt
	s_add_u32 s10, s10, 0x6000
	s_addc_u32 s11, s11, 0
	global_load_dword v33, v62, s[10:11] nt
	s_add_u32 s10, s10, 0x6000
	s_addc_u32 s11, s11, 0
	global_load_dword v34, v62, s[10:11] nt
	s_add_u32 s10, s10, 0x6000
	s_addc_u32 s11, s11, 0
	global_load_dword v35, v62, s[10:11] nt
	s_add_u32 s10, s10, 0x6000
	s_addc_u32 s11, s11, 0
	global_load_dword v36, v62, s[10:11] nt
	s_add_u32 s10, s10, 0x6000
	s_addc_u32 s11, s11, 0
	global_load_dword v37, v62, s[10:11] nt
	s_add_u32 s10, s10, 0x6000
	s_addc_u32 s11, s11, 0
	global_load_dword v70, v62, s[10:11] nt
	s_add_u32 s10, s10, 0x6000
	s_addc_u32 s11, s11, 0
	global_load_dword v71, v62, s[10:11] nt
	s_add_u32 s10, s10, 0x6000
	s_addc_u32 s11, s11, 0
	global_load_dword v72, v62, s[10:11] nt
	s_add_u32 s10, s10, 0x6000
	s_addc_u32 s11, s11, 0
	global_load_dword v73, v62, s[10:11] nt
	s_add_u32 s10, s10, 0x6000
	s_addc_u32 s11, s11, 0
	global_load_dword v74, v62, s[10:11] nt
	s_add_u32 s10, s10, 0x6000
	s_addc_u32 s11, s11, 0
	global_load_dword v75, v62, s[10:11] nt
	s_add_u32 s10, s10, 0x6000
	s_addc_u32 s11, s11, 0
	global_load_dword v76, v62, s[10:11] nt
	s_add_u32 s10, s10, 0x6000
	s_addc_u32 s11, s11, 0
	global_load_dword v77, v62, s[10:11] nt
	s_add_u32 s10, s10, 0x6000
	s_addc_u32 s11, s11, 0
	global_load_dword v78, v62, s[10:11] nt
	s_add_u32 s10, s10, 0x6000
	s_addc_u32 s11, s11, 0
	global_load_dword v79, v62, s[10:11] nt
	s_add_u32 s10, s10, 0x6000
	s_addc_u32 s11, s11, 0
	global_load_dword v80, v62, s[10:11] nt
	s_add_u32 s10, s10, 0x6000
	s_addc_u32 s11, s11, 0
	global_load_dword v81, v62, s[10:11] nt
	s_add_u32 s10, s10, 0x6000
	s_addc_u32 s11, s11, 0
	global_load_dword v82, v62, s[10:11] nt
	s_add_u32 s10, s10, 0x6000
	s_addc_u32 s11, s11, 0
	global_load_dword v83, v62, s[10:11] nt
	s_add_u32 s10, s10, 0x6000
	s_addc_u32 s11, s11, 0
	global_load_dword v84, v62, s[10:11] nt
	s_add_u32 s10, s10, 0x6000
	s_addc_u32 s11, s11, 0
	global_load_dword v85, v62, s[10:11] nt
	s_add_u32 s10, s10, 0x6000
	s_addc_u32 s11, s11, 0
	ds_read_b128 v[38:41], v86 offset:0
	ds_read_b128 v[42:45], v86 offset:4096
	ds_read_b128 v[46:49], v86 offset:8192
	ds_read_b128 v[50:53], v86 offset:12288
	ds_read_b128 v[66:69], v86 offset:16384
	s_waitcnt vmcnt(32)
	s_waitcnt lgkmcnt(4)
	v_fmac_f32_e32 v2, v6, v38
	v_fmac_f32_e32 v2, v7, v39
	v_fmac_f32_e32 v2, v8, v40
	v_fmac_f32_e32 v2, v9, v41
	ds_read_b128 v[38:41], v86 offset:16
	s_waitcnt lgkmcnt(4)
	v_fmac_f32_e32 v3, v6, v42
	v_fmac_f32_e32 v3, v7, v43
	v_fmac_f32_e32 v3, v8, v44
	v_fmac_f32_e32 v3, v9, v45
	ds_read_b128 v[42:45], v86 offset:4112
	s_waitcnt lgkmcnt(4)
	v_fmac_f32_e32 v4, v6, v46
	v_fmac_f32_e32 v4, v7, v47
	v_fmac_f32_e32 v4, v8, v48
	v_fmac_f32_e32 v4, v9, v49
	ds_read_b128 v[46:49], v86 offset:8208
	s_waitcnt lgkmcnt(4)
	v_fmac_f32_e32 v5, v6, v50
	v_fmac_f32_e32 v5, v7, v51
	v_fmac_f32_e32 v5, v8, v52
	v_fmac_f32_e32 v5, v9, v53
	ds_read_b128 v[50:53], v86 offset:12304
	s_waitcnt lgkmcnt(4)
	v_fmac_f32_e32 v63, v6, v66
	v_fmac_f32_e32 v63, v7, v67
	v_fmac_f32_e32 v63, v8, v68
	v_fmac_f32_e32 v63, v9, v69
	ds_read_b128 v[66:69], v86 offset:16400
	global_load_dword v6, v62, s[10:11] nt
	s_add_u32 s10, s10, 0x6000
	s_addc_u32 s11, s11, 0
	global_load_dword v7, v62, s[10:11] nt
	s_add_u32 s10, s10, 0x6000
	s_addc_u32 s11, s11, 0
	global_load_dword v8, v62, s[10:11] nt
	s_add_u32 s10, s10, 0x6000
	s_addc_u32 s11, s11, 0
	global_load_dword v9, v62, s[10:11] nt
	s_add_u32 s10, s10, 0x6000
	s_addc_u32 s11, s11, 0
	s_waitcnt lgkmcnt(4)
	v_fmac_f32_e32 v2, v10, v38
	v_fmac_f32_e32 v2, v11, v39
	v_fmac_f32_e32 v2, v12, v40
	v_fmac_f32_e32 v2, v13, v41
	ds_read_b128 v[38:41], v86 offset:32
	s_waitcnt lgkmcnt(4)
	v_fmac_f32_e32 v3, v10, v42
	v_fmac_f32_e32 v3, v11, v43
	v_fmac_f32_e32 v3, v12, v44
	v_fmac_f32_e32 v3, v13, v45
	ds_read_b128 v[42:45], v86 offset:4128
	s_waitcnt lgkmcnt(4)
	v_fmac_f32_e32 v4, v10, v46
	v_fmac_f32_e32 v4, v11, v47
	v_fmac_f32_e32 v4, v12, v48
	v_fmac_f32_e32 v4, v13, v49
	ds_read_b128 v[46:49], v86 offset:8224
	s_waitcnt lgkmcnt(4)
	v_fmac_f32_e32 v5, v10, v50
	v_fmac_f32_e32 v5, v11, v51
	v_fmac_f32_e32 v5, v12, v52
	v_fmac_f32_e32 v5, v13, v53
	ds_read_b128 v[50:53], v86 offset:12320
	s_waitcnt lgkmcnt(4)
	v_fmac_f32_e32 v63, v10, v66
	v_fmac_f32_e32 v63, v11, v67
	v_fmac_f32_e32 v63, v12, v68
	v_fmac_f32_e32 v63, v13, v69
	ds_read_b128 v[66:69], v86 offset:16416
	global_load_dword v10, v62, s[10:11] nt
	s_add_u32 s10, s10, 0x6000
	s_addc_u32 s11, s11, 0
	global_load_dword v11, v62, s[10:11] nt
	s_add_u32 s10, s10, 0x6000
	s_addc_u32 s11, s11, 0
	global_load_dword v12, v62, s[10:11] nt
	s_add_u32 s10, s10, 0x6000
	s_addc_u32 s11, s11, 0
	global_load_dword v13, v62, s[10:11] nt
	s_add_u32 s10, s10, 0x6000
	s_addc_u32 s11, s11, 0
	s_waitcnt lgkmcnt(4)
	v_fmac_f32_e32 v2, v14, v38
	v_fmac_f32_e32 v2, v15, v39
	v_fmac_f32_e32 v2, v16, v40
	v_fmac_f32_e32 v2, v17, v41
	ds_read_b128 v[38:41], v86 offset:48
	s_waitcnt lgkmcnt(4)
	v_fmac_f32_e32 v3, v14, v42
	v_fmac_f32_e32 v3, v15, v43
	v_fmac_f32_e32 v3, v16, v44
	v_fmac_f32_e32 v3, v17, v45
	ds_read_b128 v[42:45], v86 offset:4144
	s_waitcnt lgkmcnt(4)
	v_fmac_f32_e32 v4, v14, v46
	v_fmac_f32_e32 v4, v15, v47
	v_fmac_f32_e32 v4, v16, v48
	v_fmac_f32_e32 v4, v17, v49
	ds_read_b128 v[46:49], v86 offset:8240
	s_waitcnt lgkmcnt(4)
	v_fmac_f32_e32 v5, v14, v50
	v_fmac_f32_e32 v5, v15, v51
	v_fmac_f32_e32 v5, v16, v52
	v_fmac_f32_e32 v5, v17, v53
	ds_read_b128 v[50:53], v86 offset:12336
	s_waitcnt lgkmcnt(4)
	v_fmac_f32_e32 v63, v14, v66
	v_fmac_f32_e32 v63, v15, v67
	v_fmac_f32_e32 v63, v16, v68
	v_fmac_f32_e32 v63, v17, v69
	ds_read_b128 v[66:69], v86 offset:16432
	global_load_dword v14, v62, s[10:11] nt
	s_add_u32 s10, s10, 0x6000
	s_addc_u32 s11, s11, 0
	global_load_dword v15, v62, s[10:11] nt
	s_add_u32 s10, s10, 0x6000
	s_addc_u32 s11, s11, 0
	global_load_dword v16, v62, s[10:11] nt
	s_add_u32 s10, s10, 0x6000
	s_addc_u32 s11, s11, 0
	global_load_dword v17, v62, s[10:11] nt
	s_add_u32 s10, s10, 0x6000
	s_addc_u32 s11, s11, 0
	s_waitcnt lgkmcnt(4)
	v_fmac_f32_e32 v2, v18, v38
	v_fmac_f32_e32 v2, v19, v39
	v_fmac_f32_e32 v2, v20, v40
	v_fmac_f32_e32 v2, v21, v41
	ds_read_b128 v[38:41], v86 offset:64
	s_waitcnt lgkmcnt(4)
	v_fmac_f32_e32 v3, v18, v42
	v_fmac_f32_e32 v3, v19, v43
	v_fmac_f32_e32 v3, v20, v44
	v_fmac_f32_e32 v3, v21, v45
	ds_read_b128 v[42:45], v86 offset:4160
	s_waitcnt lgkmcnt(4)
	v_fmac_f32_e32 v4, v18, v46
	v_fmac_f32_e32 v4, v19, v47
	v_fmac_f32_e32 v4, v20, v48
	v_fmac_f32_e32 v4, v21, v49
	ds_read_b128 v[46:49], v86 offset:8256
	s_waitcnt lgkmcnt(4)
	v_fmac_f32_e32 v5, v18, v50
	v_fmac_f32_e32 v5, v19, v51
	v_fmac_f32_e32 v5, v20, v52
	v_fmac_f32_e32 v5, v21, v53
	ds_read_b128 v[50:53], v86 offset:12352
	s_waitcnt lgkmcnt(4)
	v_fmac_f32_e32 v63, v18, v66
	v_fmac_f32_e32 v63, v19, v67
	v_fmac_f32_e32 v63, v20, v68
	v_fmac_f32_e32 v63, v21, v69
	ds_read_b128 v[66:69], v86 offset:16448
	global_load_dword v18, v62, s[10:11] nt
	s_add_u32 s10, s10, 0x6000
	s_addc_u32 s11, s11, 0
	global_load_dword v19, v62, s[10:11] nt
	s_add_u32 s10, s10, 0x6000
	s_addc_u32 s11, s11, 0
	global_load_dword v20, v62, s[10:11] nt
	s_add_u32 s10, s10, 0x6000
	s_addc_u32 s11, s11, 0
	global_load_dword v21, v62, s[10:11] nt
	s_add_u32 s10, s10, 0x6000
	s_addc_u32 s11, s11, 0
	s_waitcnt vmcnt(32)
	s_waitcnt lgkmcnt(4)
	v_fmac_f32_e32 v2, v22, v38
	v_fmac_f32_e32 v2, v23, v39
	v_fmac_f32_e32 v2, v24, v40
	v_fmac_f32_e32 v2, v25, v41
	ds_read_b128 v[38:41], v86 offset:80
	s_waitcnt lgkmcnt(4)
	v_fmac_f32_e32 v3, v22, v42
	v_fmac_f32_e32 v3, v23, v43
	v_fmac_f32_e32 v3, v24, v44
	v_fmac_f32_e32 v3, v25, v45
	ds_read_b128 v[42:45], v86 offset:4176
	s_waitcnt lgkmcnt(4)
	v_fmac_f32_e32 v4, v22, v46
	v_fmac_f32_e32 v4, v23, v47
	v_fmac_f32_e32 v4, v24, v48
	v_fmac_f32_e32 v4, v25, v49
	ds_read_b128 v[46:49], v86 offset:8272
	s_waitcnt lgkmcnt(4)
	v_fmac_f32_e32 v5, v22, v50
	v_fmac_f32_e32 v5, v23, v51
	v_fmac_f32_e32 v5, v24, v52
	v_fmac_f32_e32 v5, v25, v53
	ds_read_b128 v[50:53], v86 offset:12368
	s_waitcnt lgkmcnt(4)
	v_fmac_f32_e32 v63, v22, v66
	v_fmac_f32_e32 v63, v23, v67
	v_fmac_f32_e32 v63, v24, v68
	v_fmac_f32_e32 v63, v25, v69
	ds_read_b128 v[66:69], v86 offset:16464
	global_load_dword v22, v62, s[10:11] nt
	s_add_u32 s10, s10, 0x6000
	s_addc_u32 s11, s11, 0
	global_load_dword v23, v62, s[10:11] nt
	s_add_u32 s10, s10, 0x6000
	s_addc_u32 s11, s11, 0
	global_load_dword v24, v62, s[10:11] nt
	s_add_u32 s10, s10, 0x6000
	s_addc_u32 s11, s11, 0
	global_load_dword v25, v62, s[10:11] nt
	s_add_u32 s10, s10, 0x6000
	s_addc_u32 s11, s11, 0
	s_waitcnt lgkmcnt(4)
	v_fmac_f32_e32 v2, v26, v38
	v_fmac_f32_e32 v2, v27, v39
	v_fmac_f32_e32 v2, v28, v40
	v_fmac_f32_e32 v2, v29, v41
	ds_read_b128 v[38:41], v86 offset:96
	s_waitcnt lgkmcnt(4)
	v_fmac_f32_e32 v3, v26, v42
	v_fmac_f32_e32 v3, v27, v43
	v_fmac_f32_e32 v3, v28, v44
	v_fmac_f32_e32 v3, v29, v45
	ds_read_b128 v[42:45], v86 offset:4192
	s_waitcnt lgkmcnt(4)
	v_fmac_f32_e32 v4, v26, v46
	v_fmac_f32_e32 v4, v27, v47
	v_fmac_f32_e32 v4, v28, v48
	v_fmac_f32_e32 v4, v29, v49
	ds_read_b128 v[46:49], v86 offset:8288
	s_waitcnt lgkmcnt(4)
	v_fmac_f32_e32 v5, v26, v50
	v_fmac_f32_e32 v5, v27, v51
	v_fmac_f32_e32 v5, v28, v52
	v_fmac_f32_e32 v5, v29, v53
	ds_read_b128 v[50:53], v86 offset:12384
	s_waitcnt lgkmcnt(4)
	v_fmac_f32_e32 v63, v26, v66
	v_fmac_f32_e32 v63, v27, v67
	v_fmac_f32_e32 v63, v28, v68
	v_fmac_f32_e32 v63, v29, v69
	ds_read_b128 v[66:69], v86 offset:16480
	global_load_dword v26, v62, s[10:11] nt
	s_add_u32 s10, s10, 0x6000
	s_addc_u32 s11, s11, 0
	global_load_dword v27, v62, s[10:11] nt
	s_add_u32 s10, s10, 0x6000
	s_addc_u32 s11, s11, 0
	global_load_dword v28, v62, s[10:11] nt
	s_add_u32 s10, s10, 0x6000
	s_addc_u32 s11, s11, 0
	global_load_dword v29, v62, s[10:11] nt
	s_add_u32 s10, s10, 0x6000
	s_addc_u32 s11, s11, 0
	s_waitcnt lgkmcnt(4)
	v_fmac_f32_e32 v2, v30, v38
	v_fmac_f32_e32 v2, v31, v39
	v_fmac_f32_e32 v2, v32, v40
	v_fmac_f32_e32 v2, v33, v41
	ds_read_b128 v[38:41], v86 offset:112
	s_waitcnt lgkmcnt(4)
	v_fmac_f32_e32 v3, v30, v42
	v_fmac_f32_e32 v3, v31, v43
	v_fmac_f32_e32 v3, v32, v44
	v_fmac_f32_e32 v3, v33, v45
	ds_read_b128 v[42:45], v86 offset:4208
	s_waitcnt lgkmcnt(4)
	v_fmac_f32_e32 v4, v30, v46
	v_fmac_f32_e32 v4, v31, v47
	v_fmac_f32_e32 v4, v32, v48
	v_fmac_f32_e32 v4, v33, v49
	ds_read_b128 v[46:49], v86 offset:8304
	s_waitcnt lgkmcnt(4)
	v_fmac_f32_e32 v5, v30, v50
	v_fmac_f32_e32 v5, v31, v51
	v_fmac_f32_e32 v5, v32, v52
	v_fmac_f32_e32 v5, v33, v53
	ds_read_b128 v[50:53], v86 offset:12400
	s_waitcnt lgkmcnt(4)
	v_fmac_f32_e32 v63, v30, v66
	v_fmac_f32_e32 v63, v31, v67
	v_fmac_f32_e32 v63, v32, v68
	v_fmac_f32_e32 v63, v33, v69
	ds_read_b128 v[66:69], v86 offset:16496
	global_load_dword v30, v62, s[10:11] nt
	s_add_u32 s10, s10, 0x6000
	s_addc_u32 s11, s11, 0
	global_load_dword v31, v62, s[10:11] nt
	s_add_u32 s10, s10, 0x6000
	s_addc_u32 s11, s11, 0
	global_load_dword v32, v62, s[10:11] nt
	s_add_u32 s10, s10, 0x6000
	s_addc_u32 s11, s11, 0
	global_load_dword v33, v62, s[10:11] nt
	s_add_u32 s10, s10, 0x6000
	s_addc_u32 s11, s11, 0
	s_waitcnt lgkmcnt(4)
	v_fmac_f32_e32 v2, v34, v38
	v_fmac_f32_e32 v2, v35, v39
	v_fmac_f32_e32 v2, v36, v40
	v_fmac_f32_e32 v2, v37, v41
	ds_read_b128 v[38:41], v86 offset:128
	s_waitcnt lgkmcnt(4)
	v_fmac_f32_e32 v3, v34, v42
	v_fmac_f32_e32 v3, v35, v43
	v_fmac_f32_e32 v3, v36, v44
	v_fmac_f32_e32 v3, v37, v45
	ds_read_b128 v[42:45], v86 offset:4224
	s_waitcnt lgkmcnt(4)
	v_fmac_f32_e32 v4, v34, v46
	v_fmac_f32_e32 v4, v35, v47
	v_fmac_f32_e32 v4, v36, v48
	v_fmac_f32_e32 v4, v37, v49
	ds_read_b128 v[46:49], v86 offset:8320
	s_waitcnt lgkmcnt(4)
	v_fmac_f32_e32 v5, v34, v50
	v_fmac_f32_e32 v5, v35, v51
	v_fmac_f32_e32 v5, v36, v52
	v_fmac_f32_e32 v5, v37, v53
	ds_read_b128 v[50:53], v86 offset:12416
	s_waitcnt lgkmcnt(4)
	v_fmac_f32_e32 v63, v34, v66
	v_fmac_f32_e32 v63, v35, v67
	v_fmac_f32_e32 v63, v36, v68
	v_fmac_f32_e32 v63, v37, v69
	ds_read_b128 v[66:69], v86 offset:16512
	global_load_dword v34, v62, s[10:11] nt
	s_add_u32 s10, s10, 0x6000
	s_addc_u32 s11, s11, 0
	global_load_dword v35, v62, s[10:11] nt
	s_add_u32 s10, s10, 0x6000
	s_addc_u32 s11, s11, 0
	global_load_dword v36, v62, s[10:11] nt
	s_add_u32 s10, s10, 0x6000
	s_addc_u32 s11, s11, 0
	global_load_dword v37, v62, s[10:11] nt
	s_add_u32 s10, s10, 0x6000
	s_addc_u32 s11, s11, 0
	s_waitcnt vmcnt(32)
	s_waitcnt lgkmcnt(4)
	v_fmac_f32_e32 v2, v70, v38
	v_fmac_f32_e32 v2, v71, v39
	v_fmac_f32_e32 v2, v72, v40
	v_fmac_f32_e32 v2, v73, v41
	ds_read_b128 v[38:41], v86 offset:144
	s_waitcnt lgkmcnt(4)
	v_fmac_f32_e32 v3, v70, v42
	v_fmac_f32_e32 v3, v71, v43
	v_fmac_f32_e32 v3, v72, v44
	v_fmac_f32_e32 v3, v73, v45
	ds_read_b128 v[42:45], v86 offset:4240
	s_waitcnt lgkmcnt(4)
	v_fmac_f32_e32 v4, v70, v46
	v_fmac_f32_e32 v4, v71, v47
	v_fmac_f32_e32 v4, v72, v48
	v_fmac_f32_e32 v4, v73, v49
	ds_read_b128 v[46:49], v86 offset:8336
	s_waitcnt lgkmcnt(4)
	v_fmac_f32_e32 v5, v70, v50
	v_fmac_f32_e32 v5, v71, v51
	v_fmac_f32_e32 v5, v72, v52
	v_fmac_f32_e32 v5, v73, v53
	ds_read_b128 v[50:53], v86 offset:12432
	s_waitcnt lgkmcnt(4)
	v_fmac_f32_e32 v63, v70, v66
	v_fmac_f32_e32 v63, v71, v67
	v_fmac_f32_e32 v63, v72, v68
	v_fmac_f32_e32 v63, v73, v69
	ds_read_b128 v[66:69], v86 offset:16528
	global_load_dword v70, v62, s[10:11] nt
	s_add_u32 s10, s10, 0x6000
	s_addc_u32 s11, s11, 0
	global_load_dword v71, v62, s[10:11] nt
	s_add_u32 s10, s10, 0x6000
	s_addc_u32 s11, s11, 0
	global_load_dword v72, v62, s[10:11] nt
	s_add_u32 s10, s10, 0x6000
	s_addc_u32 s11, s11, 0
	global_load_dword v73, v62, s[10:11] nt
	s_add_u32 s10, s10, 0x6000
	s_addc_u32 s11, s11, 0
	s_waitcnt lgkmcnt(4)
	v_fmac_f32_e32 v2, v74, v38
	v_fmac_f32_e32 v2, v75, v39
	v_fmac_f32_e32 v2, v76, v40
	v_fmac_f32_e32 v2, v77, v41
	ds_read_b128 v[38:41], v86 offset:160
	s_waitcnt lgkmcnt(4)
	v_fmac_f32_e32 v3, v74, v42
	v_fmac_f32_e32 v3, v75, v43
	v_fmac_f32_e32 v3, v76, v44
	v_fmac_f32_e32 v3, v77, v45
	ds_read_b128 v[42:45], v86 offset:4256
	s_waitcnt lgkmcnt(4)
	v_fmac_f32_e32 v4, v74, v46
	v_fmac_f32_e32 v4, v75, v47
	v_fmac_f32_e32 v4, v76, v48
	v_fmac_f32_e32 v4, v77, v49
	ds_read_b128 v[46:49], v86 offset:8352
	s_waitcnt lgkmcnt(4)
	v_fmac_f32_e32 v5, v74, v50
	v_fmac_f32_e32 v5, v75, v51
	v_fmac_f32_e32 v5, v76, v52
	v_fmac_f32_e32 v5, v77, v53
	ds_read_b128 v[50:53], v86 offset:12448
	s_waitcnt lgkmcnt(4)
	v_fmac_f32_e32 v63, v74, v66
	v_fmac_f32_e32 v63, v75, v67
	v_fmac_f32_e32 v63, v76, v68
	v_fmac_f32_e32 v63, v77, v69
	ds_read_b128 v[66:69], v86 offset:16544
	global_load_dword v74, v62, s[10:11] nt
	s_add_u32 s10, s10, 0x6000
	s_addc_u32 s11, s11, 0
	global_load_dword v75, v62, s[10:11] nt
	s_add_u32 s10, s10, 0x6000
	s_addc_u32 s11, s11, 0
	global_load_dword v76, v62, s[10:11] nt
	s_add_u32 s10, s10, 0x6000
	s_addc_u32 s11, s11, 0
	global_load_dword v77, v62, s[10:11] nt
	s_add_u32 s10, s10, 0x6000
	s_addc_u32 s11, s11, 0
	s_waitcnt lgkmcnt(4)
	v_fmac_f32_e32 v2, v78, v38
	v_fmac_f32_e32 v2, v79, v39
	v_fmac_f32_e32 v2, v80, v40
	v_fmac_f32_e32 v2, v81, v41
	ds_read_b128 v[38:41], v86 offset:176
	s_waitcnt lgkmcnt(4)
	v_fmac_f32_e32 v3, v78, v42
	v_fmac_f32_e32 v3, v79, v43
	v_fmac_f32_e32 v3, v80, v44
	v_fmac_f32_e32 v3, v81, v45
	ds_read_b128 v[42:45], v86 offset:4272
	s_waitcnt lgkmcnt(4)
	v_fmac_f32_e32 v4, v78, v46
	v_fmac_f32_e32 v4, v79, v47
	v_fmac_f32_e32 v4, v80, v48
	v_fmac_f32_e32 v4, v81, v49
	ds_read_b128 v[46:49], v86 offset:8368
	s_waitcnt lgkmcnt(4)
	v_fmac_f32_e32 v5, v78, v50
	v_fmac_f32_e32 v5, v79, v51
	v_fmac_f32_e32 v5, v80, v52
	v_fmac_f32_e32 v5, v81, v53
	ds_read_b128 v[50:53], v86 offset:12464
	s_waitcnt lgkmcnt(4)
	v_fmac_f32_e32 v63, v78, v66
	v_fmac_f32_e32 v63, v79, v67
	v_fmac_f32_e32 v63, v80, v68
	v_fmac_f32_e32 v63, v81, v69
	ds_read_b128 v[66:69], v86 offset:16560
	global_load_dword v78, v62, s[10:11] nt
	s_add_u32 s10, s10, 0x6000
	s_addc_u32 s11, s11, 0
	global_load_dword v79, v62, s[10:11] nt
	s_add_u32 s10, s10, 0x6000
	s_addc_u32 s11, s11, 0
	global_load_dword v80, v62, s[10:11] nt
	s_add_u32 s10, s10, 0x6000
	s_addc_u32 s11, s11, 0
	global_load_dword v81, v62, s[10:11] nt
	s_add_u32 s10, s10, 0x6000
	s_addc_u32 s11, s11, 0
	s_waitcnt lgkmcnt(4)
	v_fmac_f32_e32 v2, v82, v38
	v_fmac_f32_e32 v2, v83, v39
	v_fmac_f32_e32 v2, v84, v40
	v_fmac_f32_e32 v2, v85, v41
	ds_read_b128 v[38:41], v86 offset:192
	s_waitcnt lgkmcnt(4)
	v_fmac_f32_e32 v3, v82, v42
	v_fmac_f32_e32 v3, v83, v43
	v_fmac_f32_e32 v3, v84, v44
	v_fmac_f32_e32 v3, v85, v45
	ds_read_b128 v[42:45], v86 offset:4288
	s_waitcnt lgkmcnt(4)
	v_fmac_f32_e32 v4, v82, v46
	v_fmac_f32_e32 v4, v83, v47
	v_fmac_f32_e32 v4, v84, v48
	v_fmac_f32_e32 v4, v85, v49
	ds_read_b128 v[46:49], v86 offset:8384
	s_waitcnt lgkmcnt(4)
	v_fmac_f32_e32 v5, v82, v50
	v_fmac_f32_e32 v5, v83, v51
	v_fmac_f32_e32 v5, v84, v52
	v_fmac_f32_e32 v5, v85, v53
	ds_read_b128 v[50:53], v86 offset:12480
	s_waitcnt lgkmcnt(4)
	v_fmac_f32_e32 v63, v82, v66
	v_fmac_f32_e32 v63, v83, v67
	v_fmac_f32_e32 v63, v84, v68
	v_fmac_f32_e32 v63, v85, v69
	ds_read_b128 v[66:69], v86 offset:16576
	global_load_dword v82, v62, s[10:11] nt
	s_add_u32 s10, s10, 0x6000
	s_addc_u32 s11, s11, 0
	global_load_dword v83, v62, s[10:11] nt
	s_add_u32 s10, s10, 0x6000
	s_addc_u32 s11, s11, 0
	global_load_dword v84, v62, s[10:11] nt
	s_add_u32 s10, s10, 0x6000
	s_addc_u32 s11, s11, 0
	global_load_dword v85, v62, s[10:11] nt
	s_add_u32 s10, s10, 0x6000
	s_addc_u32 s11, s11, 0
	s_waitcnt vmcnt(32)
	s_waitcnt lgkmcnt(4)
	v_fmac_f32_e32 v2, v6, v38
	v_fmac_f32_e32 v2, v7, v39
	v_fmac_f32_e32 v2, v8, v40
	v_fmac_f32_e32 v2, v9, v41
	ds_read_b128 v[38:41], v86 offset:208
	s_waitcnt lgkmcnt(4)
	v_fmac_f32_e32 v3, v6, v42
	v_fmac_f32_e32 v3, v7, v43
	v_fmac_f32_e32 v3, v8, v44
	v_fmac_f32_e32 v3, v9, v45
	ds_read_b128 v[42:45], v86 offset:4304
	s_waitcnt lgkmcnt(4)
	v_fmac_f32_e32 v4, v6, v46
	v_fmac_f32_e32 v4, v7, v47
	v_fmac_f32_e32 v4, v8, v48
	v_fmac_f32_e32 v4, v9, v49
	ds_read_b128 v[46:49], v86 offset:8400
	s_waitcnt lgkmcnt(4)
	v_fmac_f32_e32 v5, v6, v50
	v_fmac_f32_e32 v5, v7, v51
	v_fmac_f32_e32 v5, v8, v52
	v_fmac_f32_e32 v5, v9, v53
	ds_read_b128 v[50:53], v86 offset:12496
	s_waitcnt lgkmcnt(4)
	v_fmac_f32_e32 v63, v6, v66
	v_fmac_f32_e32 v63, v7, v67
	v_fmac_f32_e32 v63, v8, v68
	v_fmac_f32_e32 v63, v9, v69
	ds_read_b128 v[66:69], v86 offset:16592
	global_load_dword v6, v62, s[10:11] nt
	s_add_u32 s10, s10, 0x6000
	s_addc_u32 s11, s11, 0
	global_load_dword v7, v62, s[10:11] nt
	s_add_u32 s10, s10, 0x6000
	s_addc_u32 s11, s11, 0
	global_load_dword v8, v62, s[10:11] nt
	s_add_u32 s10, s10, 0x6000
	s_addc_u32 s11, s11, 0
	global_load_dword v9, v62, s[10:11] nt
	s_add_u32 s10, s10, 0x6000
	s_addc_u32 s11, s11, 0
	s_waitcnt lgkmcnt(4)
	v_fmac_f32_e32 v2, v10, v38
	v_fmac_f32_e32 v2, v11, v39
	v_fmac_f32_e32 v2, v12, v40
	v_fmac_f32_e32 v2, v13, v41
	ds_read_b128 v[38:41], v86 offset:224
	s_waitcnt lgkmcnt(4)
	v_fmac_f32_e32 v3, v10, v42
	v_fmac_f32_e32 v3, v11, v43
	v_fmac_f32_e32 v3, v12, v44
	v_fmac_f32_e32 v3, v13, v45
	ds_read_b128 v[42:45], v86 offset:4320
	s_waitcnt lgkmcnt(4)
	v_fmac_f32_e32 v4, v10, v46
	v_fmac_f32_e32 v4, v11, v47
	v_fmac_f32_e32 v4, v12, v48
	v_fmac_f32_e32 v4, v13, v49
	ds_read_b128 v[46:49], v86 offset:8416
	s_waitcnt lgkmcnt(4)
	v_fmac_f32_e32 v5, v10, v50
	v_fmac_f32_e32 v5, v11, v51
	v_fmac_f32_e32 v5, v12, v52
	v_fmac_f32_e32 v5, v13, v53
	ds_read_b128 v[50:53], v86 offset:12512
	s_waitcnt lgkmcnt(4)
	v_fmac_f32_e32 v63, v10, v66
	v_fmac_f32_e32 v63, v11, v67
	v_fmac_f32_e32 v63, v12, v68
	v_fmac_f32_e32 v63, v13, v69
	ds_read_b128 v[66:69], v86 offset:16608
	global_load_dword v10, v62, s[10:11] nt
	s_add_u32 s10, s10, 0x6000
	s_addc_u32 s11, s11, 0
	global_load_dword v11, v62, s[10:11] nt
	s_add_u32 s10, s10, 0x6000
	s_addc_u32 s11, s11, 0
	global_load_dword v12, v62, s[10:11] nt
	s_add_u32 s10, s10, 0x6000
	s_addc_u32 s11, s11, 0
	global_load_dword v13, v62, s[10:11] nt
	s_add_u32 s10, s10, 0x6000
	s_addc_u32 s11, s11, 0
	s_waitcnt lgkmcnt(4)
	v_fmac_f32_e32 v2, v14, v38
	v_fmac_f32_e32 v2, v15, v39
	v_fmac_f32_e32 v2, v16, v40
	v_fmac_f32_e32 v2, v17, v41
	ds_read_b128 v[38:41], v86 offset:240
	s_waitcnt lgkmcnt(4)
	v_fmac_f32_e32 v3, v14, v42
	v_fmac_f32_e32 v3, v15, v43
	v_fmac_f32_e32 v3, v16, v44
	v_fmac_f32_e32 v3, v17, v45
	ds_read_b128 v[42:45], v86 offset:4336
	s_waitcnt lgkmcnt(4)
	v_fmac_f32_e32 v4, v14, v46
	v_fmac_f32_e32 v4, v15, v47
	v_fmac_f32_e32 v4, v16, v48
	v_fmac_f32_e32 v4, v17, v49
	ds_read_b128 v[46:49], v86 offset:8432
	s_waitcnt lgkmcnt(4)
	v_fmac_f32_e32 v5, v14, v50
	v_fmac_f32_e32 v5, v15, v51
	v_fmac_f32_e32 v5, v16, v52
	v_fmac_f32_e32 v5, v17, v53
	ds_read_b128 v[50:53], v86 offset:12528
	s_waitcnt lgkmcnt(4)
	v_fmac_f32_e32 v63, v14, v66
	v_fmac_f32_e32 v63, v15, v67
	v_fmac_f32_e32 v63, v16, v68
	v_fmac_f32_e32 v63, v17, v69
	ds_read_b128 v[66:69], v86 offset:16624
	global_load_dword v14, v62, s[10:11] nt
	s_add_u32 s10, s10, 0x6000
	s_addc_u32 s11, s11, 0
	global_load_dword v15, v62, s[10:11] nt
	s_add_u32 s10, s10, 0x6000
	s_addc_u32 s11, s11, 0
	global_load_dword v16, v62, s[10:11] nt
	s_add_u32 s10, s10, 0x6000
	s_addc_u32 s11, s11, 0
	global_load_dword v17, v62, s[10:11] nt
	s_add_u32 s10, s10, 0x6000
	s_addc_u32 s11, s11, 0
	s_waitcnt lgkmcnt(4)
	v_fmac_f32_e32 v2, v18, v38
	v_fmac_f32_e32 v2, v19, v39
	v_fmac_f32_e32 v2, v20, v40
	v_fmac_f32_e32 v2, v21, v41
	ds_read_b128 v[38:41], v86 offset:256
	s_waitcnt lgkmcnt(4)
	v_fmac_f32_e32 v3, v18, v42
	v_fmac_f32_e32 v3, v19, v43
	v_fmac_f32_e32 v3, v20, v44
	v_fmac_f32_e32 v3, v21, v45
	ds_read_b128 v[42:45], v86 offset:4352
	s_waitcnt lgkmcnt(4)
	v_fmac_f32_e32 v4, v18, v46
	v_fmac_f32_e32 v4, v19, v47
	v_fmac_f32_e32 v4, v20, v48
	v_fmac_f32_e32 v4, v21, v49
	ds_read_b128 v[46:49], v86 offset:8448
	s_waitcnt lgkmcnt(4)
	v_fmac_f32_e32 v5, v18, v50
	v_fmac_f32_e32 v5, v19, v51
	v_fmac_f32_e32 v5, v20, v52
	v_fmac_f32_e32 v5, v21, v53
	ds_read_b128 v[50:53], v86 offset:12544
	s_waitcnt lgkmcnt(4)
	v_fmac_f32_e32 v63, v18, v66
	v_fmac_f32_e32 v63, v19, v67
	v_fmac_f32_e32 v63, v20, v68
	v_fmac_f32_e32 v63, v21, v69
	ds_read_b128 v[66:69], v86 offset:16640
	global_load_dword v18, v62, s[10:11] nt
	s_add_u32 s10, s10, 0x6000
	s_addc_u32 s11, s11, 0
	global_load_dword v19, v62, s[10:11] nt
	s_add_u32 s10, s10, 0x6000
	s_addc_u32 s11, s11, 0
	global_load_dword v20, v62, s[10:11] nt
	s_add_u32 s10, s10, 0x6000
	s_addc_u32 s11, s11, 0
	global_load_dword v21, v62, s[10:11] nt
	s_add_u32 s10, s10, 0x6000
	s_addc_u32 s11, s11, 0
	s_waitcnt vmcnt(32)
	s_waitcnt lgkmcnt(4)
	v_fmac_f32_e32 v2, v22, v38
	v_fmac_f32_e32 v2, v23, v39
	v_fmac_f32_e32 v2, v24, v40
	v_fmac_f32_e32 v2, v25, v41
	ds_read_b128 v[38:41], v86 offset:272
	s_waitcnt lgkmcnt(4)
	v_fmac_f32_e32 v3, v22, v42
	v_fmac_f32_e32 v3, v23, v43
	v_fmac_f32_e32 v3, v24, v44
	v_fmac_f32_e32 v3, v25, v45
	ds_read_b128 v[42:45], v86 offset:4368
	s_waitcnt lgkmcnt(4)
	v_fmac_f32_e32 v4, v22, v46
	v_fmac_f32_e32 v4, v23, v47
	v_fmac_f32_e32 v4, v24, v48
	v_fmac_f32_e32 v4, v25, v49
	ds_read_b128 v[46:49], v86 offset:8464
	s_waitcnt lgkmcnt(4)
	v_fmac_f32_e32 v5, v22, v50
	v_fmac_f32_e32 v5, v23, v51
	v_fmac_f32_e32 v5, v24, v52
	v_fmac_f32_e32 v5, v25, v53
	ds_read_b128 v[50:53], v86 offset:12560
	s_waitcnt lgkmcnt(4)
	v_fmac_f32_e32 v63, v22, v66
	v_fmac_f32_e32 v63, v23, v67
	v_fmac_f32_e32 v63, v24, v68
	v_fmac_f32_e32 v63, v25, v69
	ds_read_b128 v[66:69], v86 offset:16656
	global_load_dword v22, v62, s[10:11] nt
	s_add_u32 s10, s10, 0x6000
	s_addc_u32 s11, s11, 0
	global_load_dword v23, v62, s[10:11] nt
	s_add_u32 s10, s10, 0x6000
	s_addc_u32 s11, s11, 0
	global_load_dword v24, v62, s[10:11] nt
	s_add_u32 s10, s10, 0x6000
	s_addc_u32 s11, s11, 0
	global_load_dword v25, v62, s[10:11] nt
	s_add_u32 s10, s10, 0x6000
	s_addc_u32 s11, s11, 0
	s_waitcnt lgkmcnt(4)
	v_fmac_f32_e32 v2, v26, v38
	v_fmac_f32_e32 v2, v27, v39
	v_fmac_f32_e32 v2, v28, v40
	v_fmac_f32_e32 v2, v29, v41
	ds_read_b128 v[38:41], v86 offset:288
	s_waitcnt lgkmcnt(4)
	v_fmac_f32_e32 v3, v26, v42
	v_fmac_f32_e32 v3, v27, v43
	v_fmac_f32_e32 v3, v28, v44
	v_fmac_f32_e32 v3, v29, v45
	ds_read_b128 v[42:45], v86 offset:4384
	s_waitcnt lgkmcnt(4)
	v_fmac_f32_e32 v4, v26, v46
	v_fmac_f32_e32 v4, v27, v47
	v_fmac_f32_e32 v4, v28, v48
	v_fmac_f32_e32 v4, v29, v49
	ds_read_b128 v[46:49], v86 offset:8480
	s_waitcnt lgkmcnt(4)
	v_fmac_f32_e32 v5, v26, v50
	v_fmac_f32_e32 v5, v27, v51
	v_fmac_f32_e32 v5, v28, v52
	v_fmac_f32_e32 v5, v29, v53
	ds_read_b128 v[50:53], v86 offset:12576
	s_waitcnt lgkmcnt(4)
	v_fmac_f32_e32 v63, v26, v66
	v_fmac_f32_e32 v63, v27, v67
	v_fmac_f32_e32 v63, v28, v68
	v_fmac_f32_e32 v63, v29, v69
	ds_read_b128 v[66:69], v86 offset:16672
	global_load_dword v26, v62, s[10:11] nt
	s_add_u32 s10, s10, 0x6000
	s_addc_u32 s11, s11, 0
	global_load_dword v27, v62, s[10:11] nt
	s_add_u32 s10, s10, 0x6000
	s_addc_u32 s11, s11, 0
	global_load_dword v28, v62, s[10:11] nt
	s_add_u32 s10, s10, 0x6000
	s_addc_u32 s11, s11, 0
	global_load_dword v29, v62, s[10:11] nt
	s_add_u32 s10, s10, 0x6000
	s_addc_u32 s11, s11, 0
	s_waitcnt lgkmcnt(4)
	v_fmac_f32_e32 v2, v30, v38
	v_fmac_f32_e32 v2, v31, v39
	v_fmac_f32_e32 v2, v32, v40
	v_fmac_f32_e32 v2, v33, v41
	ds_read_b128 v[38:41], v86 offset:304
	s_waitcnt lgkmcnt(4)
	v_fmac_f32_e32 v3, v30, v42
	v_fmac_f32_e32 v3, v31, v43
	v_fmac_f32_e32 v3, v32, v44
	v_fmac_f32_e32 v3, v33, v45
	ds_read_b128 v[42:45], v86 offset:4400
	s_waitcnt lgkmcnt(4)
	v_fmac_f32_e32 v4, v30, v46
	v_fmac_f32_e32 v4, v31, v47
	v_fmac_f32_e32 v4, v32, v48
	v_fmac_f32_e32 v4, v33, v49
	ds_read_b128 v[46:49], v86 offset:8496
	s_waitcnt lgkmcnt(4)
	v_fmac_f32_e32 v5, v30, v50
	v_fmac_f32_e32 v5, v31, v51
	v_fmac_f32_e32 v5, v32, v52
	v_fmac_f32_e32 v5, v33, v53
	ds_read_b128 v[50:53], v86 offset:12592
	s_waitcnt lgkmcnt(4)
	v_fmac_f32_e32 v63, v30, v66
	v_fmac_f32_e32 v63, v31, v67
	v_fmac_f32_e32 v63, v32, v68
	v_fmac_f32_e32 v63, v33, v69
	ds_read_b128 v[66:69], v86 offset:16688
	global_load_dword v30, v62, s[10:11] nt
	s_add_u32 s10, s10, 0x6000
	s_addc_u32 s11, s11, 0
	global_load_dword v31, v62, s[10:11] nt
	s_add_u32 s10, s10, 0x6000
	s_addc_u32 s11, s11, 0
	global_load_dword v32, v62, s[10:11] nt
	s_add_u32 s10, s10, 0x6000
	s_addc_u32 s11, s11, 0
	global_load_dword v33, v62, s[10:11] nt
	s_add_u32 s10, s10, 0x6000
	s_addc_u32 s11, s11, 0
	s_waitcnt lgkmcnt(4)
	v_fmac_f32_e32 v2, v34, v38
	v_fmac_f32_e32 v2, v35, v39
	v_fmac_f32_e32 v2, v36, v40
	v_fmac_f32_e32 v2, v37, v41
	ds_read_b128 v[38:41], v86 offset:320
	s_waitcnt lgkmcnt(4)
	v_fmac_f32_e32 v3, v34, v42
	v_fmac_f32_e32 v3, v35, v43
	v_fmac_f32_e32 v3, v36, v44
	v_fmac_f32_e32 v3, v37, v45
	ds_read_b128 v[42:45], v86 offset:4416
	s_waitcnt lgkmcnt(4)
	v_fmac_f32_e32 v4, v34, v46
	v_fmac_f32_e32 v4, v35, v47
	v_fmac_f32_e32 v4, v36, v48
	v_fmac_f32_e32 v4, v37, v49
	ds_read_b128 v[46:49], v86 offset:8512
	s_waitcnt lgkmcnt(4)
	v_fmac_f32_e32 v5, v34, v50
	v_fmac_f32_e32 v5, v35, v51
	v_fmac_f32_e32 v5, v36, v52
	v_fmac_f32_e32 v5, v37, v53
	ds_read_b128 v[50:53], v86 offset:12608
	s_waitcnt lgkmcnt(4)
	v_fmac_f32_e32 v63, v34, v66
	v_fmac_f32_e32 v63, v35, v67
	v_fmac_f32_e32 v63, v36, v68
	v_fmac_f32_e32 v63, v37, v69
	ds_read_b128 v[66:69], v86 offset:16704
	global_load_dword v34, v62, s[10:11] nt
	s_add_u32 s10, s10, 0x6000
	s_addc_u32 s11, s11, 0
	global_load_dword v35, v62, s[10:11] nt
	s_add_u32 s10, s10, 0x6000
	s_addc_u32 s11, s11, 0
	global_load_dword v36, v62, s[10:11] nt
	s_add_u32 s10, s10, 0x6000
	s_addc_u32 s11, s11, 0
	global_load_dword v37, v62, s[10:11] nt
	s_add_u32 s10, s10, 0x6000
	s_addc_u32 s11, s11, 0
	s_waitcnt vmcnt(32)
	s_waitcnt lgkmcnt(4)
	v_fmac_f32_e32 v2, v70, v38
	v_fmac_f32_e32 v2, v71, v39
	v_fmac_f32_e32 v2, v72, v40
	v_fmac_f32_e32 v2, v73, v41
	ds_read_b128 v[38:41], v86 offset:336
	s_waitcnt lgkmcnt(4)
	v_fmac_f32_e32 v3, v70, v42
	v_fmac_f32_e32 v3, v71, v43
	v_fmac_f32_e32 v3, v72, v44
	v_fmac_f32_e32 v3, v73, v45
	ds_read_b128 v[42:45], v86 offset:4432
	s_waitcnt lgkmcnt(4)
	v_fmac_f32_e32 v4, v70, v46
	v_fmac_f32_e32 v4, v71, v47
	v_fmac_f32_e32 v4, v72, v48
	v_fmac_f32_e32 v4, v73, v49
	ds_read_b128 v[46:49], v86 offset:8528
	s_waitcnt lgkmcnt(4)
	v_fmac_f32_e32 v5, v70, v50
	v_fmac_f32_e32 v5, v71, v51
	v_fmac_f32_e32 v5, v72, v52
	v_fmac_f32_e32 v5, v73, v53
	ds_read_b128 v[50:53], v86 offset:12624
	s_waitcnt lgkmcnt(4)
	v_fmac_f32_e32 v63, v70, v66
	v_fmac_f32_e32 v63, v71, v67
	v_fmac_f32_e32 v63, v72, v68
	v_fmac_f32_e32 v63, v73, v69
	ds_read_b128 v[66:69], v86 offset:16720
	s_waitcnt lgkmcnt(4)
	v_fmac_f32_e32 v2, v74, v38
	v_fmac_f32_e32 v2, v75, v39
	v_fmac_f32_e32 v2, v76, v40
	v_fmac_f32_e32 v2, v77, v41
	ds_read_b128 v[38:41], v86 offset:352
	s_waitcnt lgkmcnt(4)
	v_fmac_f32_e32 v3, v74, v42
	v_fmac_f32_e32 v3, v75, v43
	v_fmac_f32_e32 v3, v76, v44
	v_fmac_f32_e32 v3, v77, v45
	ds_read_b128 v[42:45], v86 offset:4448
	s_waitcnt lgkmcnt(4)
	v_fmac_f32_e32 v4, v74, v46
	v_fmac_f32_e32 v4, v75, v47
	v_fmac_f32_e32 v4, v76, v48
	v_fmac_f32_e32 v4, v77, v49
	ds_read_b128 v[46:49], v86 offset:8544
	s_waitcnt lgkmcnt(4)
	v_fmac_f32_e32 v5, v74, v50
	v_fmac_f32_e32 v5, v75, v51
	v_fmac_f32_e32 v5, v76, v52
	v_fmac_f32_e32 v5, v77, v53
	ds_read_b128 v[50:53], v86 offset:12640
	s_waitcnt lgkmcnt(4)
	v_fmac_f32_e32 v63, v74, v66
	v_fmac_f32_e32 v63, v75, v67
	v_fmac_f32_e32 v63, v76, v68
	v_fmac_f32_e32 v63, v77, v69
	ds_read_b128 v[66:69], v86 offset:16736
	s_waitcnt lgkmcnt(4)
	v_fmac_f32_e32 v2, v78, v38
	v_fmac_f32_e32 v2, v79, v39
	v_fmac_f32_e32 v2, v80, v40
	v_fmac_f32_e32 v2, v81, v41
	ds_read_b128 v[38:41], v86 offset:368
	s_waitcnt lgkmcnt(4)
	v_fmac_f32_e32 v3, v78, v42
	v_fmac_f32_e32 v3, v79, v43
	v_fmac_f32_e32 v3, v80, v44
	v_fmac_f32_e32 v3, v81, v45
	ds_read_b128 v[42:45], v86 offset:4464
	s_waitcnt lgkmcnt(4)
	v_fmac_f32_e32 v4, v78, v46
	v_fmac_f32_e32 v4, v79, v47
	v_fmac_f32_e32 v4, v80, v48
	v_fmac_f32_e32 v4, v81, v49
	ds_read_b128 v[46:49], v86 offset:8560
	s_waitcnt lgkmcnt(4)
	v_fmac_f32_e32 v5, v78, v50
	v_fmac_f32_e32 v5, v79, v51
	v_fmac_f32_e32 v5, v80, v52
	v_fmac_f32_e32 v5, v81, v53
	ds_read_b128 v[50:53], v86 offset:12656
	s_waitcnt lgkmcnt(4)
	v_fmac_f32_e32 v63, v78, v66
	v_fmac_f32_e32 v63, v79, v67
	v_fmac_f32_e32 v63, v80, v68
	v_fmac_f32_e32 v63, v81, v69
	ds_read_b128 v[66:69], v86 offset:16752
	s_waitcnt lgkmcnt(4)
	v_fmac_f32_e32 v2, v82, v38
	v_fmac_f32_e32 v2, v83, v39
	v_fmac_f32_e32 v2, v84, v40
	v_fmac_f32_e32 v2, v85, v41
	ds_read_b128 v[38:41], v86 offset:384
	s_waitcnt lgkmcnt(4)
	v_fmac_f32_e32 v3, v82, v42
	v_fmac_f32_e32 v3, v83, v43
	v_fmac_f32_e32 v3, v84, v44
	v_fmac_f32_e32 v3, v85, v45
	ds_read_b128 v[42:45], v86 offset:4480
	s_waitcnt lgkmcnt(4)
	v_fmac_f32_e32 v4, v82, v46
	v_fmac_f32_e32 v4, v83, v47
	v_fmac_f32_e32 v4, v84, v48
	v_fmac_f32_e32 v4, v85, v49
	ds_read_b128 v[46:49], v86 offset:8576
	s_waitcnt lgkmcnt(4)
	v_fmac_f32_e32 v5, v82, v50
	v_fmac_f32_e32 v5, v83, v51
	v_fmac_f32_e32 v5, v84, v52
	v_fmac_f32_e32 v5, v85, v53
	ds_read_b128 v[50:53], v86 offset:12672
	s_waitcnt lgkmcnt(4)
	v_fmac_f32_e32 v63, v82, v66
	v_fmac_f32_e32 v63, v83, v67
	v_fmac_f32_e32 v63, v84, v68
	v_fmac_f32_e32 v63, v85, v69
	ds_read_b128 v[66:69], v86 offset:16768
	s_waitcnt vmcnt(16)
	s_waitcnt lgkmcnt(4)
	v_fmac_f32_e32 v2, v6, v38
	v_fmac_f32_e32 v2, v7, v39
	v_fmac_f32_e32 v2, v8, v40
	v_fmac_f32_e32 v2, v9, v41
	ds_read_b128 v[38:41], v86 offset:400
	s_waitcnt lgkmcnt(4)
	v_fmac_f32_e32 v3, v6, v42
	v_fmac_f32_e32 v3, v7, v43
	v_fmac_f32_e32 v3, v8, v44
	v_fmac_f32_e32 v3, v9, v45
	ds_read_b128 v[42:45], v86 offset:4496
	s_waitcnt lgkmcnt(4)
	v_fmac_f32_e32 v4, v6, v46
	v_fmac_f32_e32 v4, v7, v47
	v_fmac_f32_e32 v4, v8, v48
	v_fmac_f32_e32 v4, v9, v49
	ds_read_b128 v[46:49], v86 offset:8592
	s_waitcnt lgkmcnt(4)
	v_fmac_f32_e32 v5, v6, v50
	v_fmac_f32_e32 v5, v7, v51
	v_fmac_f32_e32 v5, v8, v52
	v_fmac_f32_e32 v5, v9, v53
	ds_read_b128 v[50:53], v86 offset:12688
	s_waitcnt lgkmcnt(4)
	v_fmac_f32_e32 v63, v6, v66
	v_fmac_f32_e32 v63, v7, v67
	v_fmac_f32_e32 v63, v8, v68
	v_fmac_f32_e32 v63, v9, v69
	ds_read_b128 v[66:69], v86 offset:16784
	s_waitcnt lgkmcnt(4)
	v_fmac_f32_e32 v2, v10, v38
	v_fmac_f32_e32 v2, v11, v39
	v_fmac_f32_e32 v2, v12, v40
	v_fmac_f32_e32 v2, v13, v41
	ds_read_b128 v[38:41], v86 offset:416
	s_waitcnt lgkmcnt(4)
	v_fmac_f32_e32 v3, v10, v42
	v_fmac_f32_e32 v3, v11, v43
	v_fmac_f32_e32 v3, v12, v44
	v_fmac_f32_e32 v3, v13, v45
	ds_read_b128 v[42:45], v86 offset:4512
	s_waitcnt lgkmcnt(4)
	v_fmac_f32_e32 v4, v10, v46
	v_fmac_f32_e32 v4, v11, v47
	v_fmac_f32_e32 v4, v12, v48
	v_fmac_f32_e32 v4, v13, v49
	ds_read_b128 v[46:49], v86 offset:8608
	s_waitcnt lgkmcnt(4)
	v_fmac_f32_e32 v5, v10, v50
	v_fmac_f32_e32 v5, v11, v51
	v_fmac_f32_e32 v5, v12, v52
	v_fmac_f32_e32 v5, v13, v53
	ds_read_b128 v[50:53], v86 offset:12704
	s_waitcnt lgkmcnt(4)
	v_fmac_f32_e32 v63, v10, v66
	v_fmac_f32_e32 v63, v11, v67
	v_fmac_f32_e32 v63, v12, v68
	v_fmac_f32_e32 v63, v13, v69
	ds_read_b128 v[66:69], v86 offset:16800
	s_waitcnt lgkmcnt(4)
	v_fmac_f32_e32 v2, v14, v38
	v_fmac_f32_e32 v2, v15, v39
	v_fmac_f32_e32 v2, v16, v40
	v_fmac_f32_e32 v2, v17, v41
	ds_read_b128 v[38:41], v86 offset:432
	s_waitcnt lgkmcnt(4)
	v_fmac_f32_e32 v3, v14, v42
	v_fmac_f32_e32 v3, v15, v43
	v_fmac_f32_e32 v3, v16, v44
	v_fmac_f32_e32 v3, v17, v45
	ds_read_b128 v[42:45], v86 offset:4528
	s_waitcnt lgkmcnt(4)
	v_fmac_f32_e32 v4, v14, v46
	v_fmac_f32_e32 v4, v15, v47
	v_fmac_f32_e32 v4, v16, v48
	v_fmac_f32_e32 v4, v17, v49
	ds_read_b128 v[46:49], v86 offset:8624
	s_waitcnt lgkmcnt(4)
	v_fmac_f32_e32 v5, v14, v50
	v_fmac_f32_e32 v5, v15, v51
	v_fmac_f32_e32 v5, v16, v52
	v_fmac_f32_e32 v5, v17, v53
	ds_read_b128 v[50:53], v86 offset:12720
	s_waitcnt lgkmcnt(4)
	v_fmac_f32_e32 v63, v14, v66
	v_fmac_f32_e32 v63, v15, v67
	v_fmac_f32_e32 v63, v16, v68
	v_fmac_f32_e32 v63, v17, v69
	ds_read_b128 v[66:69], v86 offset:16816
	s_waitcnt lgkmcnt(4)
	v_fmac_f32_e32 v2, v18, v38
	v_fmac_f32_e32 v2, v19, v39
	v_fmac_f32_e32 v2, v20, v40
	v_fmac_f32_e32 v2, v21, v41
	ds_read_b128 v[38:41], v86 offset:448
	s_waitcnt lgkmcnt(4)
	v_fmac_f32_e32 v3, v18, v42
	v_fmac_f32_e32 v3, v19, v43
	v_fmac_f32_e32 v3, v20, v44
	v_fmac_f32_e32 v3, v21, v45
	ds_read_b128 v[42:45], v86 offset:4544
	s_waitcnt lgkmcnt(4)
	v_fmac_f32_e32 v4, v18, v46
	v_fmac_f32_e32 v4, v19, v47
	v_fmac_f32_e32 v4, v20, v48
	v_fmac_f32_e32 v4, v21, v49
	ds_read_b128 v[46:49], v86 offset:8640
	s_waitcnt lgkmcnt(4)
	v_fmac_f32_e32 v5, v18, v50
	v_fmac_f32_e32 v5, v19, v51
	v_fmac_f32_e32 v5, v20, v52
	v_fmac_f32_e32 v5, v21, v53
	ds_read_b128 v[50:53], v86 offset:12736
	s_waitcnt lgkmcnt(4)
	v_fmac_f32_e32 v63, v18, v66
	v_fmac_f32_e32 v63, v19, v67
	v_fmac_f32_e32 v63, v20, v68
	v_fmac_f32_e32 v63, v21, v69
	ds_read_b128 v[66:69], v86 offset:16832
	s_waitcnt vmcnt(0)
	s_waitcnt lgkmcnt(4)
	v_fmac_f32_e32 v2, v22, v38
	v_fmac_f32_e32 v2, v23, v39
	v_fmac_f32_e32 v2, v24, v40
	v_fmac_f32_e32 v2, v25, v41
	ds_read_b128 v[38:41], v86 offset:464
	s_waitcnt lgkmcnt(4)
	v_fmac_f32_e32 v3, v22, v42
	v_fmac_f32_e32 v3, v23, v43
	v_fmac_f32_e32 v3, v24, v44
	v_fmac_f32_e32 v3, v25, v45
	ds_read_b128 v[42:45], v86 offset:4560
	s_waitcnt lgkmcnt(4)
	v_fmac_f32_e32 v4, v22, v46
	v_fmac_f32_e32 v4, v23, v47
	v_fmac_f32_e32 v4, v24, v48
	v_fmac_f32_e32 v4, v25, v49
	ds_read_b128 v[46:49], v86 offset:8656
	s_waitcnt lgkmcnt(4)
	v_fmac_f32_e32 v5, v22, v50
	v_fmac_f32_e32 v5, v23, v51
	v_fmac_f32_e32 v5, v24, v52
	v_fmac_f32_e32 v5, v25, v53
	ds_read_b128 v[50:53], v86 offset:12752
	s_waitcnt lgkmcnt(4)
	v_fmac_f32_e32 v63, v22, v66
	v_fmac_f32_e32 v63, v23, v67
	v_fmac_f32_e32 v63, v24, v68
	v_fmac_f32_e32 v63, v25, v69
	ds_read_b128 v[66:69], v86 offset:16848
	s_waitcnt lgkmcnt(4)
	v_fmac_f32_e32 v2, v26, v38
	v_fmac_f32_e32 v2, v27, v39
	v_fmac_f32_e32 v2, v28, v40
	v_fmac_f32_e32 v2, v29, v41
	ds_read_b128 v[38:41], v86 offset:480
	s_waitcnt lgkmcnt(4)
	v_fmac_f32_e32 v3, v26, v42
	v_fmac_f32_e32 v3, v27, v43
	v_fmac_f32_e32 v3, v28, v44
	v_fmac_f32_e32 v3, v29, v45
	ds_read_b128 v[42:45], v86 offset:4576
	s_waitcnt lgkmcnt(4)
	v_fmac_f32_e32 v4, v26, v46
	v_fmac_f32_e32 v4, v27, v47
	v_fmac_f32_e32 v4, v28, v48
	v_fmac_f32_e32 v4, v29, v49
	ds_read_b128 v[46:49], v86 offset:8672
	s_waitcnt lgkmcnt(4)
	v_fmac_f32_e32 v5, v26, v50
	v_fmac_f32_e32 v5, v27, v51
	v_fmac_f32_e32 v5, v28, v52
	v_fmac_f32_e32 v5, v29, v53
	ds_read_b128 v[50:53], v86 offset:12768
	s_waitcnt lgkmcnt(4)
	v_fmac_f32_e32 v63, v26, v66
	v_fmac_f32_e32 v63, v27, v67
	v_fmac_f32_e32 v63, v28, v68
	v_fmac_f32_e32 v63, v29, v69
	ds_read_b128 v[66:69], v86 offset:16864
	s_waitcnt lgkmcnt(4)
	v_fmac_f32_e32 v2, v30, v38
	v_fmac_f32_e32 v2, v31, v39
	v_fmac_f32_e32 v2, v32, v40
	v_fmac_f32_e32 v2, v33, v41
	ds_read_b128 v[38:41], v86 offset:496
	s_waitcnt lgkmcnt(4)
	v_fmac_f32_e32 v3, v30, v42
	v_fmac_f32_e32 v3, v31, v43
	v_fmac_f32_e32 v3, v32, v44
	v_fmac_f32_e32 v3, v33, v45
	ds_read_b128 v[42:45], v86 offset:4592
	s_waitcnt lgkmcnt(4)
	v_fmac_f32_e32 v4, v30, v46
	v_fmac_f32_e32 v4, v31, v47
	v_fmac_f32_e32 v4, v32, v48
	v_fmac_f32_e32 v4, v33, v49
	ds_read_b128 v[46:49], v86 offset:8688
	s_waitcnt lgkmcnt(4)
	v_fmac_f32_e32 v5, v30, v50
	v_fmac_f32_e32 v5, v31, v51
	v_fmac_f32_e32 v5, v32, v52
	v_fmac_f32_e32 v5, v33, v53
	ds_read_b128 v[50:53], v86 offset:12784
	s_waitcnt lgkmcnt(4)
	v_fmac_f32_e32 v63, v30, v66
	v_fmac_f32_e32 v63, v31, v67
	v_fmac_f32_e32 v63, v32, v68
	v_fmac_f32_e32 v63, v33, v69
	ds_read_b128 v[66:69], v86 offset:16880
	s_waitcnt lgkmcnt(4)
	v_fmac_f32_e32 v2, v34, v38
	v_fmac_f32_e32 v2, v35, v39
	v_fmac_f32_e32 v2, v36, v40
	v_fmac_f32_e32 v2, v37, v41
	s_waitcnt lgkmcnt(3)
	v_fmac_f32_e32 v3, v34, v42
	v_fmac_f32_e32 v3, v35, v43
	v_fmac_f32_e32 v3, v36, v44
	v_fmac_f32_e32 v3, v37, v45
	s_waitcnt lgkmcnt(2)
	v_fmac_f32_e32 v4, v34, v46
	v_fmac_f32_e32 v4, v35, v47
	v_fmac_f32_e32 v4, v36, v48
	v_fmac_f32_e32 v4, v37, v49
	s_waitcnt lgkmcnt(1)
	v_fmac_f32_e32 v5, v34, v50
	v_fmac_f32_e32 v5, v35, v51
	v_fmac_f32_e32 v5, v36, v52
	v_fmac_f32_e32 v5, v37, v53
	s_waitcnt lgkmcnt(0)
	v_fmac_f32_e32 v63, v34, v66
	v_fmac_f32_e32 v63, v35, v67
	v_fmac_f32_e32 v63, v36, v68
	v_fmac_f32_e32 v63, v37, v69
	s_mul_i32 s5, s18, 0x500
	v_add_u32_e32 v0, s5, v55
	ds_write2st64_b32 v0, v2, v3 offset0:80 offset1:81
	ds_write2st64_b32 v0, v4, v5 offset0:82 offset1:83
	ds_write_b32 v0, v63 offset:21504
	s_waitcnt lgkmcnt(0)
	s_barrier
	s_and_saveexec_b64 s[8:9], s[6:7]
	s_cbranch_execz .LBB0_570
	s_load_dwordx2 s[10:11], s[0:1], 0x28
	s_mul_i32 s5, s15, 0x1800
	s_add_i32 s5, s5, s4
	v_or_b32_e32 v2, s5, v54
	v_ashrrev_i32_e32 v3, 31, v2
	s_waitcnt lgkmcnt(0)
	v_lshl_add_u64 v[2:3], v[2:3], 2, s[10:11]
	global_load_dword v0, v[2:3], off
	ds_read2st64_b32 v[2:3], v59 offset0:80 offset1:85
	ds_read2st64_b32 v[4:5], v59 offset0:90 offset1:95
	ds_read2st64_b32 v[6:7], v59 offset0:100 offset1:105
	ds_read2st64_b32 v[8:9], v59 offset0:110 offset1:115
	v_mad_u64_u32 v[10:11], s[10:11], s15, 5, v[58:59]
	s_movk_i32 s5, 0x1800
	v_mul_lo_u32 v10, v10, s5
	v_add_u32_e32 v10, s4, v10
	v_or_b32_e32 v10, v10, v54
	v_readlane_b32 s4, v255, 48
	v_ashrrev_i32_e32 v11, 31, v10
	v_readlane_b32 s5, v255, 49
	s_waitcnt vmcnt(0) lgkmcnt(3)
	v_add_f32_e32 v0, v0, v2
	v_add_f32_e32 v0, v0, v3
	s_waitcnt lgkmcnt(2)
	v_add_f32_e32 v0, v0, v4
	v_add_f32_e32 v0, v0, v5
	s_waitcnt lgkmcnt(1)
	v_add_f32_e32 v0, v0, v6
	v_add_f32_e32 v0, v0, v7
	s_waitcnt lgkmcnt(0)
	v_add_f32_e32 v0, v0, v8
	v_add_f32_e32 v0, v0, v9
	v_lshl_add_u64 v[2:3], v[10:11], 2, s[4:5]
	global_store_dword v[2:3], v0, off
	s_branch .LBB0_570
